# plus scan loaders: removed run-time-redundant guard waits in the item-load stage (they stalled on the fragment loads of the previous iteration)
# baseline (speedup 1.0000x reference)
; __device__ __forceinline__ TItem titem_decode(const Params& P, int l, int r) {
;     ...
;     const int nblk = t.N / 32, kb = item / nblk, nb = item - kb * nblk; t.k0 = 64 * kb; t.n0 = 32 * nb;
;     return t;
; }
.LBB0_678:
	s_lshr_b32 s20, s15, 5
	v_cvt_f32_u32_e32 v2, s20
	s_sub_i32 s23, 0, s20
	s_abs_i32 s22, s14
	s_ashr_i32 s21, s14, 31
	v_rcp_iflag_f32_e32 v2, v2
	s_nop 0
	v_mul_f32_e32 v2, 0x4f7ffffe, v2
	v_cvt_u32_f32_e32 v2, v2
	s_nop 0
	v_readfirstlane_b32 s48, v2
	s_mul_i32 s23, s23, s48
	s_mul_hi_u32 s23, s48, s23
	s_add_i32 s48, s48, s23
	s_mul_hi_u32 s23, s22, s48
	s_mul_i32 s48, s23, s20
	s_sub_i32 s22, s22, s48
	s_add_i32 s48, s23, 1
	s_sub_i32 s68, s22, s20
	s_cmp_ge_u32 s22, s20
	s_cselect_b32 s23, s48, s23
	s_cselect_b32 s22, s68, s22
	s_add_i32 s48, s23, 1
	s_cmp_ge_u32 s22, s20
	s_cselect_b32 s22, s48, s23
	s_xor_b32 s22, s22, s21
	s_sub_i32 s21, s22, s21
	s_mul_i32 s20, s21, s20
	s_sub_i32 s14, s14, s20
	s_lshl_b32 s21, s21, 6
	s_lshl_b32 s20, s14, 5
	v_or_b32_e32 v2, s21, v49
	s_ashr_i32 s14, s21, 31
	s_mul_i32 s14, s14, s15
	v_mad_u64_u32 v[66:67], s[22:23], v2, s15, 0
	v_add_u32_e32 v67, s14, v67
	v_lshl_add_u64 v[66:67], v[66:67], 2, s[18:19]
	s_ashr_i32 s21, s20, 31
	v_lshl_add_u64 v[66:67], s[20:21], 2, v[66:67]
	v_lshlrev_b32_e32 v2, 2, v50
	v_lshl_add_u64 v[66:67], v[66:67], 0, v[2:3]
	s_lshl_b32 s86, s15, 1
	v_lshl_add_u64 v[72:73], s[86:87], 2, v[66:67]
	s_lshl_b32 s86, s15, 2
	v_lshl_add_u64 v[74:75], s[86:87], 2, v[66:67]
	s_mul_i32 s86, s15, 6
	global_load_dword v71, v[66:67], off nt
	s_mov_b64 s[18:19], -1
	global_load_dword v72, v[72:73], off nt
	s_mov_b32 s22, s97
	global_load_dword v73, v[74:75], off nt
	v_lshl_add_u64 v[74:75], s[86:87], 2, v[66:67]
	s_lshl_b32 s86, s15, 3
	v_lshl_add_u64 v[76:77], s[86:87], 2, v[66:67]
	s_mul_i32 s86, s15, 10
	global_load_dword v74, v[74:75], off nt
	s_nop 0
	global_load_dword v75, v[76:77], off nt
	v_lshl_add_u64 v[76:77], s[86:87], 2, v[66:67]
	s_mul_i32 s86, s15, 12
	v_lshl_add_u64 v[78:79], s[86:87], 2, v[66:67]
	s_mul_i32 s86, s15, 14
	global_load_dword v76, v[76:77], off nt
	s_nop 0
	global_load_dword v77, v[78:79], off nt
	v_lshl_add_u64 v[78:79], s[86:87], 2, v[66:67]
	s_lshl_b32 s86, s15, 4
	v_lshl_add_u64 v[80:81], s[86:87], 2, v[66:67]
	s_mul_i32 s86, s15, 18
	global_load_dword v78, v[78:79], off nt
	s_nop 0
	global_load_dword v79, v[80:81], off nt
	v_lshl_add_u64 v[80:81], s[86:87], 2, v[66:67]
	s_mul_i32 s86, s15, 20
	v_lshl_add_u64 v[82:83], s[86:87], 2, v[66:67]
	s_mul_i32 s86, s15, 22
	global_load_dword v80, v[80:81], off nt
	s_nop 0
	global_load_dword v81, v[82:83], off nt
	v_lshl_add_u64 v[82:83], s[86:87], 2, v[66:67]
	s_mul_i32 s86, s15, 24
	v_lshl_add_u64 v[84:85], s[86:87], 2, v[66:67]
	s_mul_i32 s86, s15, 26
	global_load_dword v82, v[82:83], off nt
	s_nop 0
	global_load_dword v83, v[84:85], off nt
	v_lshl_add_u64 v[84:85], s[86:87], 2, v[66:67]
	s_mul_i32 s86, s15, 28
	v_lshl_add_u64 v[86:87], s[86:87], 2, v[66:67]
	s_mul_i32 s86, s15, 30
	global_load_dword v84, v[84:85], off nt
	s_nop 0
	global_load_dword v85, v[86:87], off nt
	v_lshl_add_u64 v[86:87], s[86:87], 2, v[66:67]
	s_lshl_b32 s86, s15, 5
	v_lshl_add_u64 v[88:89], s[86:87], 2, v[66:67]
	s_mul_i32 s86, s15, 34
	global_load_dword v86, v[86:87], off nt
	s_nop 0
	global_load_dword v87, v[88:89], off nt
	v_lshl_add_u64 v[88:89], s[86:87], 2, v[66:67]
	s_mul_i32 s86, s15, 36
	v_lshl_add_u64 v[100:101], s[86:87], 2, v[66:67]
	s_mul_i32 s86, s15, 38
	global_load_dword v88, v[88:89], off nt
	s_nop 0
	global_load_dword v89, v[100:101], off nt
	v_lshl_add_u64 v[100:101], s[86:87], 2, v[66:67]
	s_mul_i32 s86, s15, 40
	global_load_dword v99, v[100:101], off nt
	v_lshl_add_u64 v[100:101], s[86:87], 2, v[66:67]
	s_mul_i32 s86, s15, 42
	v_lshl_add_u64 v[102:103], s[86:87], 2, v[66:67]
	s_mul_i32 s86, s15, 44
	global_load_dword v100, v[100:101], off nt
	s_nop 0
	global_load_dword v101, v[102:103], off nt
	v_lshl_add_u64 v[102:103], s[86:87], 2, v[66:67]
	s_mul_i32 s86, s15, 46
	v_lshl_add_u64 v[104:105], s[86:87], 2, v[66:67]
	s_mul_i32 s86, s15, 48
	global_load_dword v102, v[102:103], off nt
	s_nop 0
	global_load_dword v103, v[104:105], off nt
	v_lshl_add_u64 v[104:105], s[86:87], 2, v[66:67]
	s_mul_i32 s86, s15, 50
	v_lshl_add_u64 v[106:107], s[86:87], 2, v[66:67]
	s_mul_i32 s86, s15, 52
	global_load_dword v104, v[104:105], off nt
	s_nop 0
	global_load_dword v105, v[106:107], off nt
	v_lshl_add_u64 v[106:107], s[86:87], 2, v[66:67]
	s_mul_i32 s86, s15, 54
	v_lshl_add_u64 v[108:109], s[86:87], 2, v[66:67]
	s_mul_i32 s86, s15, 56
	global_load_dword v106, v[106:107], off nt
	s_nop 0
	global_load_dword v107, v[108:109], off nt
	v_lshl_add_u64 v[108:109], s[86:87], 2, v[66:67]
	s_mul_i32 s86, s15, 58
	v_lshl_add_u64 v[110:111], s[86:87], 2, v[66:67]
	s_mul_i32 s86, s15, 60
	global_load_dword v108, v[108:109], off nt
	s_nop 0
	global_load_dword v109, v[110:111], off nt
	v_lshl_add_u64 v[110:111], s[86:87], 2, v[66:67]
	s_mul_i32 s86, s15, 62
	v_lshl_add_u64 v[66:67], s[86:87], 2, v[66:67]
	global_load_dword v110, v[110:111], off nt
	s_nop 0
	global_load_dword v66, v[66:67], off nt

; __device__ __forceinline__ TItem titem_decode(const Params& P, int l, int r) {
;     ...
;     const int nblk = t.N / 32, kb = item / nblk, nb = item - kb * nblk; t.k0 = 64 * kb; t.n0 = 32 * nb;
;     return t;
; }
.LBB0_729:
	s_lshr_b32 s15, s14, 5
	v_cvt_f32_u32_e32 v0, s15
	s_sub_i32 s22, 0, s15
	s_abs_i32 s21, s93
	s_ashr_i32 s20, s93, 31
	v_rcp_iflag_f32_e32 v0, v0
	v_lshlrev_b32_e32 v2, 2, v50
	v_mul_f32_e32 v0, 0x4f7ffffe, v0
	v_cvt_u32_f32_e32 v0, v0
	s_nop 0
	v_readfirstlane_b32 s23, v0
	s_mul_i32 s22, s22, s23
	s_mul_hi_u32 s22, s23, s22
	s_add_i32 s23, s23, s22
	s_mul_hi_u32 s22, s21, s23
	s_mul_i32 s23, s22, s15
	s_sub_i32 s21, s21, s23
	s_add_i32 s23, s22, 1
	s_sub_i32 s48, s21, s15
	s_cmp_ge_u32 s21, s15
	s_cselect_b32 s22, s23, s22
	s_cselect_b32 s21, s48, s21
	s_add_i32 s23, s22, 1
	s_cmp_ge_u32 s21, s15
	s_cselect_b32 s21, s23, s22
	s_xor_b32 s21, s21, s20
	s_sub_i32 s20, s21, s20
	s_mul_i32 s15, s20, s15
	s_sub_i32 s15, s93, s15
	s_lshl_b32 s21, s20, 6
	s_lshl_b32 s20, s15, 5
	v_or_b32_e32 v0, s21, v49
	s_ashr_i32 s15, s21, 31
	s_mul_i32 s15, s15, s14
	v_mad_u64_u32 v[0:1], s[22:23], v0, s14, 0
	v_add_u32_e32 v1, s15, v1
	v_lshl_add_u64 v[0:1], v[0:1], 2, s[18:19]
	s_ashr_i32 s21, s20, 31
	v_lshl_add_u64 v[0:1], s[20:21], 2, v[0:1]
	v_lshl_add_u64 v[0:1], v[0:1], 0, v[2:3]
	s_lshl_b32 s86, s14, 1
	v_lshl_add_u64 v[100:101], s[86:87], 2, v[0:1]
	s_lshl_b32 s86, s14, 2
	v_lshl_add_u64 v[102:103], s[86:87], 2, v[0:1]
	s_mul_i32 s86, s14, 6
	global_load_dword v99, v[0:1], off nt
	s_mov_b64 s[18:19], -1
	global_load_dword v100, v[100:101], off nt
	s_mov_b32 s15, s92
	global_load_dword v101, v[102:103], off nt
	v_lshl_add_u64 v[102:103], s[86:87], 2, v[0:1]
	s_lshl_b32 s86, s14, 3
	v_lshl_add_u64 v[104:105], s[86:87], 2, v[0:1]
	s_mul_i32 s86, s14, 10
	global_load_dword v102, v[102:103], off nt
	s_nop 0
	global_load_dword v103, v[104:105], off nt
	v_lshl_add_u64 v[104:105], s[86:87], 2, v[0:1]
	s_mul_i32 s86, s14, 12
	v_lshl_add_u64 v[106:107], s[86:87], 2, v[0:1]
	s_mul_i32 s86, s14, 14
	global_load_dword v104, v[104:105], off nt
	s_nop 0
	global_load_dword v105, v[106:107], off nt
	v_lshl_add_u64 v[106:107], s[86:87], 2, v[0:1]
	s_lshl_b32 s86, s14, 4
	v_lshl_add_u64 v[108:109], s[86:87], 2, v[0:1]
	s_mul_i32 s86, s14, 18
	global_load_dword v106, v[106:107], off nt
	s_nop 0
	global_load_dword v107, v[108:109], off nt
	v_lshl_add_u64 v[108:109], s[86:87], 2, v[0:1]
	s_mul_i32 s86, s14, 20
	v_lshl_add_u64 v[110:111], s[86:87], 2, v[0:1]
	s_mul_i32 s86, s14, 22
	global_load_dword v108, v[108:109], off nt
	s_nop 0
	global_load_dword v109, v[110:111], off nt
	v_lshl_add_u64 v[110:111], s[86:87], 2, v[0:1]
	s_mul_i32 s86, s14, 24
	v_lshl_add_u64 v[112:113], s[86:87], 2, v[0:1]
	s_mul_i32 s86, s14, 26
	global_load_dword v110, v[110:111], off nt
	s_nop 0
	global_load_dword v111, v[112:113], off nt
	v_lshl_add_u64 v[112:113], s[86:87], 2, v[0:1]
	s_mul_i32 s86, s14, 28
	v_lshl_add_u64 v[114:115], s[86:87], 2, v[0:1]
	s_mul_i32 s86, s14, 30
	global_load_dword v112, v[112:113], off nt
	s_nop 0
	global_load_dword v113, v[114:115], off nt
	v_lshl_add_u64 v[114:115], s[86:87], 2, v[0:1]
	s_lshl_b32 s86, s14, 5
	v_lshl_add_u64 v[116:117], s[86:87], 2, v[0:1]
	s_mul_i32 s86, s14, 34
	global_load_dword v114, v[114:115], off nt
	s_nop 0
	global_load_dword v115, v[116:117], off nt
	v_lshl_add_u64 v[116:117], s[86:87], 2, v[0:1]
	s_mul_i32 s86, s14, 36
	v_lshl_add_u64 v[118:119], s[86:87], 2, v[0:1]
	s_mul_i32 s86, s14, 38
	global_load_dword v116, v[116:117], off nt
	s_nop 0
	global_load_dword v117, v[118:119], off nt
	v_lshl_add_u64 v[118:119], s[86:87], 2, v[0:1]
	s_mul_i32 s86, s14, 40
	v_lshl_add_u64 v[120:121], s[86:87], 2, v[0:1]
	s_mul_i32 s86, s14, 42
	global_load_dword v118, v[118:119], off nt
	s_nop 0
	global_load_dword v119, v[120:121], off nt
	v_lshl_add_u64 v[120:121], s[86:87], 2, v[0:1]
	s_mul_i32 s86, s14, 44
	v_lshl_add_u64 v[122:123], s[86:87], 2, v[0:1]
	s_mul_i32 s86, s14, 46
	global_load_dword v120, v[120:121], off nt
	s_nop 0
	global_load_dword v121, v[122:123], off nt
	v_lshl_add_u64 v[122:123], s[86:87], 2, v[0:1]
	s_mul_i32 s86, s14, 48
	v_lshl_add_u64 v[124:125], s[86:87], 2, v[0:1]
	s_mul_i32 s86, s14, 50
	global_load_dword v122, v[122:123], off nt
	s_nop 0
	global_load_dword v123, v[124:125], off nt
	v_lshl_add_u64 v[124:125], s[86:87], 2, v[0:1]
	s_mul_i32 s86, s14, 52
	v_lshl_add_u64 v[126:127], s[86:87], 2, v[0:1]
	s_mul_i32 s86, s14, 54
	global_load_dword v124, v[124:125], off nt
	s_nop 0
	global_load_dword v125, v[126:127], off nt
	v_lshl_add_u64 v[126:127], s[86:87], 2, v[0:1]
	s_mul_i32 s86, s14, 56
	v_lshl_add_u64 v[128:129], s[86:87], 2, v[0:1]
	s_mul_i32 s86, s14, 58
	global_load_dword v126, v[126:127], off nt
	s_nop 0
	global_load_dword v127, v[128:129], off nt
	v_lshl_add_u64 v[128:129], s[86:87], 2, v[0:1]
	s_mul_i32 s86, s14, 60
	v_lshl_add_u64 v[130:131], s[86:87], 2, v[0:1]
	s_mul_i32 s86, s14, 62
	v_lshl_add_u64 v[0:1], s[86:87], 2, v[0:1]
	global_load_dword v128, v[128:129], off nt
	s_nop 0
	global_load_dword v129, v[130:131], off nt
	s_nop 0
	global_load_dword v130, v[0:1], off nt
